# opt14
# speedup vs baseline: 1.0654x; 1.0093x over previous
; __device__ void convT(const Ctx& cx, const float* __restrict__ W, int K, int Nsrc, u16* __restrict__ dst, int Np, bool mapc, char* shm) {
;     ...
;   const int tid = fresh_tid(cx.wave_s);
;   const int nkt = K >> 6, nnt = Np >> 6, ntile = nkt * nnt;
;   for (int t = cx.bid; t < ntile; t += cx.nb) {
;     const int n0 = (t / nkt) << 6, k0 = (t % nkt) << 6;
;     const int nn = tid & 63;
;     const int col = mapc ? map_col(n0 + nn) : (n0 + nn);
;     __syncthreads();
; #pragma unroll
;     for (int i = 0; i < 8; ++i) {
;       const int kk = (tid >> 6) + 8 * i;
;       float v = (col >= 0) ? __builtin_nontemporal_load(&W[(size_t)(k0 + kk) * Nsrc + col]) : 0.f;
;       tile[nn * 66 + kk] = f2b(v);
;     }
;     __syncthreads();
;     const int nn2 = tid >> 3, kc = (tid & 7) * 8;
;     const uint32_t* src = (const uint32_t*)(tile + nn2 * 66 + kc);
;     uint4 o; o.x = src[0]; o.y = src[1]; o.z = src[2]; o.w = src[3];
;     { const u32x4_t ov = {o.x, o.y, o.z, o.w}; __builtin_nontemporal_store(ov, (u32x4_t*)(dst + (size_t)(n0 + nn2) * K + k0 + kc)); }
;   }
.LBB0_1346:
	s_andn2_b64 vcc, exec, s[42:43]
	s_mov_b32 s33, 0
	s_cbranch_vccnz .LBB0_1407
	v_mbcnt_lo_u32_b32 v0, -1, s33
	v_mbcnt_hi_u32_b32 v0, -1, v0
	v_lshlrev_b32_e32 v2, 5, v0
	v_and_b32_e32 v2, 32, v2
	v_lshrrev_b32_e32 v6, 1, v0
	v_or_b32_e32 v5, 0x2310, v2
	v_and_or_b32 v2, v6, 31, v2
	s_mul_i32 s4, s74, 0xb6b0000
	v_add_u32_e32 v1, s1, v0
	v_and_b32_e32 v4, 63, v0
	v_add_u32_e32 v6, 0xffffc810, v2
	v_lshlrev_b32_e32 v2, 6, v0
	v_lshlrev_b32_e32 v0, 3, v0
	s_waitcnt lgkmcnt(0)
	s_add_u32 s4, s28, s4
	v_ashrrev_i32_e32 v9, 3, v1
	v_and_b32_e32 v0, 56, v0
	s_movk_i32 s0, 0x84
	s_addc_u32 s5, s29, 0
	s_mul_i32 s50, s74, 0x6000000
	v_ashrrev_i32_e32 v8, 6, v1
	v_mul_lo_u32 v1, v9, s0
	v_lshlrev_b32_e32 v10, 1, v0
	s_add_u32 s50, s8, s50
	v_and_b32_e32 v2, 64, v2
	v_mul_u32_u24_e32 v12, 0x84, v4
	v_add3_u32 v10, 0, v1, v10
	v_lshlrev_b32_e32 v1, 1, v8
	v_readlane_b32 s52, v254, 17
	v_readlane_b32 s0, v254, 19
	s_addc_u32 s51, s9, 0
	v_or_b32_e32 v7, 0x2010, v2
	v_or_b32_e32 v11, 16, v2
	v_add3_u32 v12, 0, v12, v1
	s_lshl_b32 s33, s52, 6
	s_lshl_b32 s56, s0, 6
	v_lshlrev_b32_e32 v2, 1, v0
	s_mov_b32 s57, s52
	v_readlane_b32 s53, v254, 18
	v_readlane_b32 s64, v254, 16
	v_readlane_b32 s65, v254, 19
	s_nop 1
	s_mul_i32 s66, s64, s65
	s_add_i32 s57, s57, s66
	s_lshl_b32 s33, s57, 6
	s_lshl_b32 s56, s65, 9
	s_mul_i32 s66, s64, 0x2100
	s_addk_i32 s66, 0x2100
	v_mul_u32_u24_e32 v27, 0x84, v4
	v_add_u32_e32 v27, s66, v27
	v_lshrrev_b32_e32 v9, 3, v4
	v_mul_u32_u24_e32 v26, 0x84, v9
	v_add3_u32 v26, s66, v26, v2
	s_branch .LBB0_1349
.LBB0_1348:
	s_or_b64 exec, exec, s[52:53]
	s_waitcnt lgkmcnt(0)
	s_mov_b32 s64, 0
.Lmy_j_in:
	s_mul_i32 s65, s64, 0x420
	v_add_u32_e32 v10, s65, v26
	ds_read2_b32 v[14:15], v10 offset1:1
	ds_read2_b32 v[16:17], v10 offset0:2 offset1:3
	s_lshl_b32 s65, s64, 3
	s_add_i32 s65, s65, s58
	v_add_u32_e32 v0, s65, v9
	v_ashrrev_i32_e32 v1, 31, v0
	s_add_i32 s52, s33, s54
	v_lshlrev_b64 v[0:1], 12, v[0:1]
	v_lshl_add_u64 v[0:1], s[50:51], 0, v[0:1]
	s_ashr_i32 s53, s52, 31
	v_lshl_add_u64 v[0:1], s[52:53], 1, v[0:1]
	v_lshl_add_u64 v[0:1], v[0:1], 0, v[2:3]
	s_waitcnt lgkmcnt(0)
	global_store_dwordx4 v[0:1], v[14:17], off nt
	s_add_i32 s64, s64, 1
	s_cmp_lt_u32 s64, 8
	s_cbranch_scc1 .Lmy_j_in
	v_readlane_b32 s0, v254, 19
	s_nop 1
	s_lshl_b32 s0, s0, 3
	s_add_i32 s57, s57, s0
	s_add_i32 s33, s33, s56
	s_cmpk_lt_i32 s57, 0x2e00
	s_cbranch_scc0 .LBB0_1407

; __device__ void convT(const Ctx& cx, const float* __restrict__ W, int K, int Nsrc, u16* __restrict__ dst, int Np, bool mapc, char* shm) {
;     ...
;   for (int t = cx.bid; t < ntile; t += cx.nb) {
;     const int n0 = (t / nkt) << 6, k0 = (t % nkt) << 6;
;     const int nn = tid & 63;
;     const int col = mapc ? map_col(n0 + nn) : (n0 + nn);
;     __syncthreads();
; #pragma unroll
;     for (int i = 0; i < 8; ++i) {
;       const int kk = (tid >> 6) + 8 * i;
;       float v = (col >= 0) ? __builtin_nontemporal_load(&W[(size_t)(k0 + kk) * Nsrc + col]) : 0.f;
;       tile[nn * 66 + kk] = f2b(v);
;     }
.LBB0_1403:
	s_or_b64 exec, exec, s[52:53]
	v_cmp_gt_i32_e32 vcc, 0, v0
	v_mov_b32_e32 v28, v0
	s_and_saveexec_b64 s[52:53], vcc
	s_xor_b64 s[52:53], exec, s[52:53]
	s_cbranch_execz .LBB0_1405
	ds_write2_b32 v27, v3, v3 offset0:0 offset1:1
	ds_write2_b32 v27, v3, v3 offset0:2 offset1:3
	ds_write2_b32 v27, v3, v3 offset0:4 offset1:5
	ds_write2_b32 v27, v3, v3 offset0:6 offset1:7
	ds_write2_b32 v27, v3, v3 offset0:8 offset1:9
	ds_write2_b32 v27, v3, v3 offset0:10 offset1:11
	ds_write2_b32 v27, v3, v3 offset0:12 offset1:13
	ds_write2_b32 v27, v3, v3 offset0:14 offset1:15
	ds_write2_b32 v27, v3, v3 offset0:16 offset1:17
	ds_write2_b32 v27, v3, v3 offset0:18 offset1:19
	ds_write2_b32 v27, v3, v3 offset0:20 offset1:21
	ds_write2_b32 v27, v3, v3 offset0:22 offset1:23
	ds_write2_b32 v27, v3, v3 offset0:24 offset1:25
	ds_write2_b32 v27, v3, v3 offset0:26 offset1:27
	ds_write2_b32 v27, v3, v3 offset0:28 offset1:29
	ds_write2_b32 v27, v3, v3 offset0:30 offset1:31
.LBB0_1405:
	s_or_saveexec_b64 s[52:53], s[52:53]
	s_lshl_b32 s54, s59, 11
	s_sub_i32 s54, 0, s54
	v_mov_b32_e32 v1, 0
	v_mov_b32_e32 v13, 0
	v_mov_b32_e32 v14, 0
	v_mov_b32_e32 v15, 0
	s_xor_b64 exec, exec, s[52:53]
	s_cbranch_execz .LBB0_1348
	s_mov_b32 s64, 0
.Lmy_g_in:
	v_mov_b32_e32 v0, v28
	v_mov_b32_e32 v8, s64
	s_lshl_b32 s65, s64, 1
	v_add_u32_e32 v12, s65, v27
	s_add_i32 s55, s54, s33
	v_mov_b32_e32 v1, v3
	v_add_u32_e32 v13, s55, v8
	v_lshl_add_u64 v[0:1], v[0:1], 2, s[4:5]
	s_mov_b32 s0, 0x16d60
	v_add_u32_e32 v16, 8, v13
	v_add_u32_e32 v18, 16, v13
	v_add_u32_e32 v20, 24, v13
	v_mad_i64_i32 v[14:15], s[60:61], v13, s0, v[0:1]
	v_mad_i64_i32 v[16:17], s[60:61], v16, s0, v[0:1]
	v_mad_i64_i32 v[18:19], s[60:61], v18, s0, v[0:1]
	v_mad_i64_i32 v[20:21], s[60:61], v20, s0, v[0:1]
	global_load_dword v22, v[14:15], off nt
	global_load_dword v23, v[16:17], off nt
	global_load_dword v24, v[18:19], off nt
	s_nop 0
	global_load_dword v20, v[20:21], off nt
	v_add_u32_e32 v14, 32, v13
	v_add_u32_e32 v16, 40, v13
	v_add_u32_e32 v18, 48, v13
	v_add_u32_e32 v13, 56, v13
	v_mad_i64_i32 v[14:15], s[60:61], v14, s0, v[0:1]
	v_mad_i64_i32 v[16:17], s[60:61], v16, s0, v[0:1]
	v_mad_i64_i32 v[18:19], s[60:61], v18, s0, v[0:1]
	v_mad_i64_i32 v[0:1], s[60:61], v13, s0, v[0:1]
	global_load_dword v14, v[14:15], off nt
	s_nop 0
	global_load_dword v15, v[16:17], off nt
	s_nop 0
	global_load_dword v16, v[18:19], off nt
	s_waitcnt vmcnt(0)
	v_cvt_pk_bf16_f32 v17, v23, s0
	global_load_dword v0, v[0:1], off nt
	v_cvt_pk_bf16_f32 v1, v22, s0
	ds_write_b16 v12, v1
	v_cvt_pk_bf16_f32 v18, v24, s0
	v_cvt_pk_bf16_f32 v19, v20, s0
	ds_write_b16 v12, v17 offset:16
	ds_write_b16 v12, v18 offset:32
	ds_write_b16 v12, v19 offset:48
	v_cvt_pk_bf16_f32 v1, v14, s0
	v_cvt_pk_bf16_f32 v13, v15, s0
	v_cvt_pk_bf16_f32 v14, v16, s0
	s_waitcnt vmcnt(0)
	v_cvt_pk_bf16_f32 v15, v0, s0
	ds_write_b16 v12, v1 offset:64
	ds_write_b16 v12, v13 offset:80
	ds_write_b16 v12, v14 offset:96
	ds_write_b16 v12, v15 offset:112
	s_add_i32 s64, s64, 1
	s_cmp_lt_u32 s64, 8
	s_cbranch_scc1 .Lmy_g_in
	s_branch .LBB0_1348

; __device__ void convT(const Ctx& cx, const float* __restrict__ W, int K, int Nsrc, u16* __restrict__ dst, int Np, bool mapc, char* shm) {
;     ...
;   const int tid = fresh_tid(cx.wave_s);
;   const int nkt = K >> 6, nnt = Np >> 6, ntile = nkt * nnt;
;   for (int t = cx.bid; t < ntile; t += cx.nb) {
;     const int n0 = (t / nkt) << 6, k0 = (t % nkt) << 6;
;     const int nn = tid & 63;
;     const int col = mapc ? map_col(n0 + nn) : (n0 + nn);
;     __syncthreads();
; #pragma unroll
;     for (int i = 0; i < 8; ++i) {
;       const int kk = (tid >> 6) + 8 * i;
;       float v = (col >= 0) ? __builtin_nontemporal_load(&W[(size_t)(k0 + kk) * Nsrc + col]) : 0.f;
;       tile[nn * 66 + kk] = f2b(v);
;     }
;     __syncthreads();
;     const int nn2 = tid >> 3, kc = (tid & 7) * 8;
;     const uint32_t* src = (const uint32_t*)(tile + nn2 * 66 + kc);
;     uint4 o; o.x = src[0]; o.y = src[1]; o.z = src[2]; o.w = src[3];
;     { const u32x4_t ov = {o.x, o.y, o.z, o.w}; __builtin_nontemporal_store(ov, (u32x4_t*)(dst + (size_t)(n0 + nn2) * K + k0 + kc)); }
;   }
.LBB0_1435:
	v_cndmask_b32_e64 v0, 0, 1, s[46:47]
	s_lshl_b64 s[50:51], s[74:75], 24
	v_cmp_ne_u32_e64 s[4:5], 1, v0
	s_andn2_b64 vcc, exec, s[46:47]
	s_mov_b32 s33, 0
	s_cbranch_vccnz .LBB0_1442
	v_mbcnt_lo_u32_b32 v0, -1, s33
	v_mbcnt_hi_u32_b32 v2, -1, v0
	s_lshl_b64 s[52:53], s[50:51], 2
	v_add_u32_e32 v4, s1, v2
	v_and_b32_e32 v0, 63, v2
	v_lshlrev_b32_e32 v2, 3, v2
	s_add_u32 s52, s36, s52
	v_ashrrev_i32_e32 v1, 6, v4
	v_ashrrev_i32_e32 v4, 3, v4
	v_and_b32_e32 v2, 56, v2
	s_movk_i32 s0, 0x84
	s_addc_u32 s53, s37, s53
	s_lshl_b64 s[54:55], s[50:51], 1
	v_mul_lo_u32 v5, v4, s0
	v_lshlrev_b32_e32 v7, 1, v2
	s_add_u32 s54, s14, s54
	v_mul_u32_u24_e32 v6, 0x84, v0
	v_add3_u32 v5, 0, v5, v7
	v_lshlrev_b32_e32 v7, 1, v1
	v_readlane_b32 s56, v254, 17
	v_readlane_b32 s0, v254, 19
	s_addc_u32 s55, s15, s55
	v_add3_u32 v6, 0, v6, v7
	s_lshl_b32 s33, s56, 6
	s_lshl_b32 s58, s0, 6
	v_lshlrev_b32_e32 v2, 1, v2
	s_mov_b32 s59, s56
	v_readlane_b32 s57, v254, 18
	v_readlane_b32 s64, v254, 16
	v_readlane_b32 s65, v254, 19
	s_nop 1
	s_mul_i32 s66, s64, s65
	s_add_i32 s59, s59, s66
	s_lshl_b32 s33, s59, 6
	s_lshl_b32 s58, s65, 9
	s_mul_i32 s66, s64, 0x2100
	s_addk_i32 s66, 0x2100
	v_mul_u32_u24_e32 v27, 0x84, v0
	v_add_u32_e32 v27, s66, v27
	v_lshrrev_b32_e32 v4, 3, v0
	v_mul_u32_u24_e32 v26, 0x84, v4
	v_add3_u32 v26, s66, v26, v2
	s_branch .LBB0_1438
.LBB0_1437:
	s_waitcnt lgkmcnt(0)
	s_mov_b32 s64, 0
.Lmy_j_up:
	s_mul_i32 s65, s64, 0x420
	v_add_u32_e32 v5, s65, v26
	ds_read2_b32 v[8:9], v5 offset1:1
	ds_read2_b32 v[10:11], v5 offset0:2 offset1:3
	s_lshl_b32 s65, s64, 3
	s_add_i32 s65, s65, s60
	v_add_u32_e32 v12, s65, v4
	v_ashrrev_i32_e32 v13, 31, v12
	s_add_i32 s56, s33, s61
	v_lshlrev_b64 v[12:13], 12, v[12:13]
	v_lshl_add_u64 v[12:13], s[54:55], 0, v[12:13]
	s_ashr_i32 s57, s56, 31
	v_lshl_add_u64 v[12:13], s[56:57], 1, v[12:13]
	v_lshl_add_u64 v[12:13], v[12:13], 0, v[2:3]
	s_waitcnt lgkmcnt(0)
	global_store_dwordx4 v[12:13], v[8:11], off nt
	s_add_i32 s64, s64, 1
	s_cmp_lt_u32 s64, 8
	s_cbranch_scc1 .Lmy_j_up
	v_readlane_b32 s0, v254, 19
	s_nop 1
	s_lshl_b32 s0, s0, 3
	s_add_i32 s59, s59, s0
	s_add_i32 s33, s33, s58
	s_cmpk_lt_i32 s59, 0x1000
	s_cbranch_scc0 .LBB0_1442
.LBB0_1438:
	s_ashr_i32 s56, s59, 31
	s_lshr_b32 s56, s56, 27
	s_add_i32 s56, s59, s56
	s_ashr_i32 s61, s56, 5
	s_lshl_b32 s60, s61, 6
	s_cmp_lt_i32 s60, 0
	s_mov_b64 s[56:57], -1
	s_cbranch_scc0 .LBB0_1440
	ds_write_b16 v6, v3
	ds_write_b16 v6, v3 offset:16
	ds_write_b16 v6, v3 offset:32
	ds_write_b16 v6, v3 offset:48
	s_mov_b64 s[56:57], 0
.LBB0_1440:
	s_lshl_b32 s61, s61, 11
	s_sub_i32 s61, 0, s61
	v_mov_b32_e32 v7, 0
	s_andn2_b64 vcc, exec, s[56:57]
	v_mov_b32_e32 v8, 0
	v_mov_b32_e32 v9, 0
	v_mov_b32_e32 v10, 0
	s_cbranch_vccnz .LBB0_1437
	s_mov_b32 s64, 0
.Lmy_g_up:
	v_mov_b32_e32 v1, s64
	s_lshl_b32 s65, s64, 1
	v_add_u32_e32 v6, s65, v27
	s_add_i32 s56, s61, s33
	v_add_u32_e32 v10, s56, v1
	v_ashrrev_i32_e32 v11, 31, v10
	v_lshlrev_b64 v[12:13], 15, v[10:11]
	v_add_u32_e32 v14, 8, v10
	v_add_u32_e32 v16, 16, v10
	v_add_u32_e32 v18, 24, v10
	v_add_u32_e32 v20, 32, v10
	v_add_u32_e32 v22, 40, v10
	v_add_u32_e32 v24, 48, v10
	v_add_u32_e32 v10, 56, v10
	v_or_b32_e32 v8, s60, v0
	v_mov_b32_e32 v9, v3
	v_ashrrev_i32_e32 v15, 31, v14
	v_ashrrev_i32_e32 v17, 31, v16
	v_ashrrev_i32_e32 v19, 31, v18
	v_ashrrev_i32_e32 v21, 31, v20
	v_ashrrev_i32_e32 v23, 31, v22
	v_ashrrev_i32_e32 v25, 31, v24
	v_ashrrev_i32_e32 v11, 31, v10
	v_lshl_add_u64 v[8:9], v[8:9], 2, s[52:53]
	v_lshlrev_b64 v[14:15], 15, v[14:15]
	v_lshlrev_b64 v[16:17], 15, v[16:17]
	v_lshlrev_b64 v[18:19], 15, v[18:19]
	v_lshlrev_b64 v[20:21], 15, v[20:21]
	v_lshlrev_b64 v[22:23], 15, v[22:23]
	v_lshlrev_b64 v[24:25], 15, v[24:25]
	v_lshlrev_b64 v[10:11], 15, v[10:11]
	v_lshl_add_u64 v[12:13], v[8:9], 0, v[12:13]
	v_lshl_add_u64 v[14:15], v[8:9], 0, v[14:15]
	v_lshl_add_u64 v[16:17], v[8:9], 0, v[16:17]
	v_lshl_add_u64 v[18:19], v[8:9], 0, v[18:19]
	v_lshl_add_u64 v[20:21], v[8:9], 0, v[20:21]
	v_lshl_add_u64 v[22:23], v[8:9], 0, v[22:23]
	v_lshl_add_u64 v[24:25], v[8:9], 0, v[24:25]
	v_lshl_add_u64 v[8:9], v[8:9], 0, v[10:11]
	global_load_dword v7, v[12:13], off nt
	s_nop 0
	global_load_dword v12, v[14:15], off nt
	global_load_dword v13, v[16:17], off nt
	s_nop 0
	global_load_dword v14, v[18:19], off nt
	global_load_dword v15, v[20:21], off nt
	global_load_dword v16, v[22:23], off nt
	global_load_dword v17, v[24:25], off nt
	global_load_dword v10, v[8:9], off nt
	s_waitcnt vmcnt(0)
	v_cvt_pk_bf16_f32 v7, v7, s0
	v_cvt_pk_bf16_f32 v11, v12, s0
	ds_write_b16 v6, v7
	v_cvt_pk_bf16_f32 v12, v13, s0
	v_cvt_pk_bf16_f32 v7, v15, s0
	v_cvt_pk_bf16_f32 v8, v16, s0
	v_cvt_pk_bf16_f32 v9, v17, s0
	v_cvt_pk_bf16_f32 v10, v10, s0
	v_cvt_pk_bf16_f32 v13, v14, s0
	ds_write_b16 v6, v11 offset:16
	ds_write_b16 v6, v12 offset:32
	ds_write_b16 v6, v13 offset:48
	ds_write_b16 v6, v7 offset:64
	ds_write_b16 v6, v8 offset:80
	ds_write_b16 v6, v9 offset:96
	ds_write_b16 v6, v10 offset:112
	s_add_i32 s64, s64, 1
	s_cmp_lt_u32 s64, 8
	s_cbranch_scc1 .Lmy_g_up
	s_branch .LBB0_1437
.LBB0_1442:
	s_and_b64 vcc, exec, s[4:5]
	s_mov_b32 s33, 0
	s_cbranch_vccnz .LBB0_1345
	v_mbcnt_lo_u32_b32 v0, -1, s33
	v_mbcnt_hi_u32_b32 v2, -1, v0
	s_lshl_b64 s[4:5], s[50:51], 2
	v_add_u32_e32 v4, s1, v2
	v_and_b32_e32 v0, 63, v2
	v_lshlrev_b32_e32 v2, 3, v2
	s_add_u32 s4, s38, s4
	v_ashrrev_i32_e32 v1, 6, v4
	v_ashrrev_i32_e32 v4, 3, v4
	v_and_b32_e32 v2, 56, v2
	s_movk_i32 s0, 0x84
	s_addc_u32 s5, s39, s5
	s_lshl_b64 s[50:51], s[50:51], 1
	v_mul_lo_u32 v5, v4, s0
	v_lshlrev_b32_e32 v7, 1, v2
	s_add_u32 s50, s40, s50
	v_mul_u32_u24_e32 v6, 0x84, v0
	v_add3_u32 v5, 0, v5, v7
	v_lshlrev_b32_e32 v7, 1, v1
	v_readlane_b32 s52, v254, 17
	v_readlane_b32 s0, v254, 19
	s_addc_u32 s51, s41, s51
	v_add3_u32 v6, 0, v6, v7
	s_lshl_b32 s33, s52, 6
	s_lshl_b32 s54, s0, 6
	v_lshlrev_b32_e32 v2, 1, v2
	s_mov_b32 s55, s52
	v_readlane_b32 s53, v254, 18
	v_readlane_b32 s64, v254, 16
	v_readlane_b32 s65, v254, 19
	s_nop 1
	s_mul_i32 s66, s64, s65
	s_add_i32 s55, s55, s66
	s_lshl_b32 s33, s55, 6
	s_lshl_b32 s54, s65, 9
	s_mul_i32 s66, s64, 0x2100
	s_addk_i32 s66, 0x2100
	v_mul_u32_u24_e32 v27, 0x84, v0
	v_add_u32_e32 v27, s66, v27
	v_lshrrev_b32_e32 v4, 3, v0
	v_mul_u32_u24_e32 v26, 0x84, v4
	v_add3_u32 v26, s66, v26, v2
	s_branch .LBB0_1445

; __device__ void convT(const Ctx& cx, const float* __restrict__ W, int K, int Nsrc, u16* __restrict__ dst, int Np, bool mapc, char* shm) {
;     ...
;   for (int t = cx.bid; t < ntile; t += cx.nb) {
;     const int n0 = (t / nkt) << 6, k0 = (t % nkt) << 6;
;     const int nn = tid & 63;
;     const int col = mapc ? map_col(n0 + nn) : (n0 + nn);
;     __syncthreads();
; #pragma unroll
;     for (int i = 0; i < 8; ++i) {
;       const int kk = (tid >> 6) + 8 * i;
;       float v = (col >= 0) ? __builtin_nontemporal_load(&W[(size_t)(k0 + kk) * Nsrc + col]) : 0.f;
;       tile[nn * 66 + kk] = f2b(v);
;     }
;     __syncthreads();
;     const int nn2 = tid >> 3, kc = (tid & 7) * 8;
;     const uint32_t* src = (const uint32_t*)(tile + nn2 * 66 + kc);
;     uint4 o; o.x = src[0]; o.y = src[1]; o.z = src[2]; o.w = src[3];
;     { const u32x4_t ov = {o.x, o.y, o.z, o.w}; __builtin_nontemporal_store(ov, (u32x4_t*)(dst + (size_t)(n0 + nn2) * K + k0 + kc)); }
.Lmy_j_dn:
	s_mul_i32 s65, s64, 0x420
	v_add_u32_e32 v5, s65, v26
	ds_read2_b32 v[8:9], v5 offset1:1
	ds_read2_b32 v[10:11], v5 offset0:2 offset1:3
	s_lshl_b32 s65, s64, 3
	s_add_i32 s65, s65, s56
	v_add_u32_e32 v12, s65, v4
	v_ashrrev_i32_e32 v13, 31, v12
	s_add_i32 s52, s33, s57
	v_lshlrev_b64 v[12:13], 14, v[12:13]
	v_lshl_add_u64 v[12:13], s[50:51], 0, v[12:13]
	s_ashr_i32 s53, s52, 31
	v_lshl_add_u64 v[12:13], s[52:53], 1, v[12:13]
	v_lshl_add_u64 v[12:13], v[12:13], 0, v[2:3]
	s_waitcnt lgkmcnt(0)
	global_store_dwordx4 v[12:13], v[8:11], off nt
	s_add_i32 s64, s64, 1
	s_cmp_lt_u32 s64, 8
	s_cbranch_scc1 .Lmy_j_dn
	v_readlane_b32 s0, v254, 19
	s_nop 1
	s_lshl_b32 s0, s0, 3
	s_add_i32 s55, s55, s0
	s_add_i32 s33, s33, s54
	s_cmpk_lt_i32 s55, 0x1000
	s_cbranch_scc0 .LBB0_1345
.LBB0_1445:
	s_cmpk_lt_i32 s55, 0xff81
	s_mov_b64 s[52:53], -1
	s_cbranch_scc0 .LBB0_1447
	ds_write_b16 v6, v3
	ds_write_b16 v6, v3 offset:16
	ds_write_b16 v6, v3 offset:32
	ds_write_b16 v6, v3 offset:48
	s_mov_b64 s[52:53], 0
.LBB0_1447:
	s_ashr_i32 s56, s55, 31
	s_lshr_b32 s56, s56, 25
	s_add_i32 s56, s55, s56
	s_ashr_i32 s57, s56, 7
	s_lshl_b32 s56, s57, 6
	s_lshl_b32 s57, s57, 13
	s_sub_i32 s57, 0, s57
	v_mov_b32_e32 v7, 0
	s_andn2_b64 vcc, exec, s[52:53]
	v_mov_b32_e32 v8, 0
	v_mov_b32_e32 v9, 0
	v_mov_b32_e32 v10, 0
	s_cbranch_vccnz .LBB0_1444
	s_mov_b32 s64, 0
.Lmy_g_dn:
	v_mov_b32_e32 v1, s64
	s_lshl_b32 s65, s64, 1
	v_add_u32_e32 v6, s65, v27
	s_add_i32 s52, s57, s33
	v_add_u32_e32 v10, s52, v1
	v_ashrrev_i32_e32 v11, 31, v10
	v_lshlrev_b64 v[12:13], 13, v[10:11]
	v_add_u32_e32 v14, 8, v10
	v_add_u32_e32 v16, 16, v10
	v_add_u32_e32 v18, 24, v10
	v_add_u32_e32 v20, 32, v10
	v_add_u32_e32 v22, 40, v10
	v_add_u32_e32 v24, 48, v10
	v_add_u32_e32 v10, 56, v10
	v_or_b32_e32 v8, s56, v0
	v_mov_b32_e32 v9, v3
	v_ashrrev_i32_e32 v15, 31, v14
	v_ashrrev_i32_e32 v17, 31, v16
	v_ashrrev_i32_e32 v19, 31, v18
	v_ashrrev_i32_e32 v21, 31, v20
	v_ashrrev_i32_e32 v23, 31, v22
	v_ashrrev_i32_e32 v25, 31, v24
	v_ashrrev_i32_e32 v11, 31, v10
	v_lshl_add_u64 v[8:9], v[8:9], 2, s[4:5]
	v_lshlrev_b64 v[14:15], 13, v[14:15]
	v_lshlrev_b64 v[16:17], 13, v[16:17]
	v_lshlrev_b64 v[18:19], 13, v[18:19]
	v_lshlrev_b64 v[20:21], 13, v[20:21]
	v_lshlrev_b64 v[22:23], 13, v[22:23]
	v_lshlrev_b64 v[24:25], 13, v[24:25]
	v_lshlrev_b64 v[10:11], 13, v[10:11]
	v_lshl_add_u64 v[12:13], v[8:9], 0, v[12:13]
	v_lshl_add_u64 v[14:15], v[8:9], 0, v[14:15]
	v_lshl_add_u64 v[16:17], v[8:9], 0, v[16:17]
	v_lshl_add_u64 v[18:19], v[8:9], 0, v[18:19]
	v_lshl_add_u64 v[20:21], v[8:9], 0, v[20:21]
	v_lshl_add_u64 v[22:23], v[8:9], 0, v[22:23]
	v_lshl_add_u64 v[24:25], v[8:9], 0, v[24:25]
	v_lshl_add_u64 v[8:9], v[8:9], 0, v[10:11]
	global_load_dword v7, v[12:13], off nt
	s_nop 0
	global_load_dword v12, v[14:15], off nt
	global_load_dword v13, v[16:17], off nt
	s_nop 0
	global_load_dword v14, v[18:19], off nt
	global_load_dword v15, v[20:21], off nt
	global_load_dword v16, v[22:23], off nt
	global_load_dword v17, v[24:25], off nt
	global_load_dword v10, v[8:9], off nt
	s_waitcnt vmcnt(0)
	v_cvt_pk_bf16_f32 v7, v7, s0
	v_cvt_pk_bf16_f32 v11, v12, s0
	ds_write_b16 v6, v7
	v_cvt_pk_bf16_f32 v12, v13, s0
	v_cvt_pk_bf16_f32 v7, v15, s0
	v_cvt_pk_bf16_f32 v8, v16, s0
	v_cvt_pk_bf16_f32 v9, v17, s0
	v_cvt_pk_bf16_f32 v10, v10, s0
	v_cvt_pk_bf16_f32 v13, v14, s0
	ds_write_b16 v6, v11 offset:16
	ds_write_b16 v6, v12 offset:32
	ds_write_b16 v6, v13 offset:48
	ds_write_b16 v6, v7 offset:64
	ds_write_b16 v6, v8 offset:80
	ds_write_b16 v6, v9 offset:96
	ds_write_b16 v6, v10 offset:112
	s_add_i32 s64, s64, 1
	s_cmp_lt_u32 s64, 8
	s_cbranch_scc1 .Lmy_g_dn
	s_branch .LBB0_1444
